# weight transposes split 2 items in the GLU phase + 6 in out_proj per idle workgroup (GLU phase no longer waits for them); write-back restored at the barrier after out_proj
# baseline (speedup 1.0000x reference)
.Lp7_tr:
	s_mov_b64 s[16:17], s[0:1]
	s_load_dwordx2 s[18:19], s[0:1], 0xe8
	s_sub_i32 s28, s2, 0x40
	s_movk_i32 s45, 0x40
	s_movk_i32 s32, 0x1ff
	s_branch .Lp6_common
.Lp6_tr:
	s_mov_b64 s[16:17], s[0:1]
	s_load_dwordx2 s[18:19], s[0:1], 0xe8
	s_sub_i32 s28, s2, 0xc0
	s_movk_i32 s45, 0x40
	s_movk_i32 s32, 0x7f

.Lp6_ret:
	s_mov_b64 exec, -1
	s_cmpk_eq_i32 s32, 0x7f
	s_cbranch_scc1 .LBB0_1182
	s_mov_b64 s[14:15], 0
	s_branch .LBB0_1246
